# GEMM K-loops: leading half reads the B1 fragments after barrier a under its first MFMA block (SP1 load part 16 -> 12 reads)
# baseline (speedup 1.0000x reference)
; #define PG8_STAGE(bufoff, gbase, voff) do { _Pragma("unroll") for (int _i = 0; _i < 2; ++_i) \
;         __builtin_amdgcn_global_load_lds((const unsigned*)((const char*)(gbase) + (voff)[_i]), (PG8_LAS unsigned*)(lds + (bufoff) + ldsw + _i * 8192), 16, 0, 0); } while (0)
; #define PG8_LDA(dst, b, h) do { _Pragma("unroll") for (int m = 0; m < 4; ++m) _Pragma("unroll") for (int k = 0; k < 2; ++k) dst[m][k] = *(const PG8_LAS bf16x8*)(lds + PG8_SA(b, h) + aoff + m * 2048 + k * 1024); } while (0)
; #define PG8_LDB(dst, b, h) do { _Pragma("unroll") for (int n = 0; n < 2; ++n) _Pragma("unroll") for (int k = 0; k < 2; ++k) dst[n][k] = *(const PG8_LAS bf16x8*)(lds + PG8_SB(b, h) + boff + n * 2048 + k * 1024); } while (0)
; #define PG8_MMA(ai, bj, At, Bt) do { __builtin_amdgcn_s_setprio(1); _Pragma("unroll") for (int m = 0; m < 4; ++m) _Pragma("unroll") for (int n = 0; n < 2; ++n) _Pragma("unroll") for (int k = 0; k < 2; ++k) \
;         acc[ai][bj][m][n] = __builtin_amdgcn_mfma_f32_16x16x32_bf16(Bt[n][k], At[m][k], acc[ai][bj][m][n], 0, 0, 0); __builtin_amdgcn_s_setprio(0); } while (0)
; #define PG8_WAIT_V(n) asm volatile("s_waitcnt vmcnt(" #n ")" ::: "memory")
; #define PG8_WAIT_L(n) asm volatile("s_waitcnt lgkmcnt(" #n ")" ::: "memory")
; #define PG8_BAR __builtin_amdgcn_s_barrier()
; #define PG8_SCHED __builtin_amdgcn_sched_barrier(0)
; template <class Epi, class Sched, bool ALIGN_EPI = false, bool SP2 = false>
; __device__ __forceinline__ void gemm_phase(PG8_LAS unsigned char* lds, const Gemm g, const Sched& S, const Epi& E, int tid_in) {
;     ...
;             PG8_LDB(B0, 0, 0); PG8_LDB(B1, 0, 1); PG8_SCHED; PG8_LDA(At, 0, 0); PG8_STAGE(PG8_SA(1, 1), a1 + hstep, voffA);
;             PG8_WAIT_V(8); PG8_WAIT_L(0); PG8_BAR; PG8_MMA(0, 0, At, B0); PG8_MMA(0, 1, At, B1); PG8_BAR; PG8_SCHED;
;             PG8_LDA(At, 0, 1); PG8_STAGE(PG8_SB(0, 0), b2, voffB); PG8_STAGE(PG8_SB(0, 1), b2 + hstep, voffB); PG8_STAGE(PG8_SA(0, 0), a2, voffA);
;             PG8_WAIT_V(8); PG8_WAIT_L(0); PG8_BAR; PG8_MMA(1, 0, At, B0); PG8_MMA(1, 1, At, B1); PG8_BAR; PG8_SCHED;
.LBB0_577:
	s_mov_b64 vcc, s[22:23]
	ds_read_b128 v[128:131], v212
	ds_read_b128 v[132:135], v212 offset:1024
	ds_read_b128 v[136:139], v212 offset:2048
	ds_read_b128 v[140:143], v212 offset:3072
	s_cbranch_vccnz .Lb1a_577_0
	ds_read_b128 v[144:147], v213
	ds_read_b128 v[148:151], v213 offset:1024
	ds_read_b128 v[152:155], v213 offset:2048
	ds_read_b128 v[156:159], v213 offset:3072
.Lb1a_577_0:
	s_add_u32 s8, s6, 0xfff00080
	s_addc_u32 s9, s7, -1
	s_cmp_eq_u32 s43, 60
	s_cselect_b32 s41, s1, s9
	s_cselect_b32 s40, s2, s8
	s_cselect_b32 s9, s5, s42
	s_cselect_b32 s8, s29, s31
	v_lshl_add_u64 v[204:205], s[6:7], 0, v[178:179]
	s_add_i32 m0, s48, 0xc000
	ds_read_b128 v[160:163], v214
	ds_read_b128 v[184:187], v214 offset:1024
	ds_read_b128 v[188:191], v214 offset:2048
	ds_read_b128 v[192:195], v214 offset:3072
	ds_read_b128 v[196:199], v214 offset:4096
	ds_read_b128 v[200:203], v214 offset:5120
	ds_read_b128 v[216:219], v214 offset:6144
	ds_read_b128 v[220:223], v214 offset:7168
	global_load_lds_dwordx4 v[204:205], off
	v_lshl_add_u64 v[204:205], s[6:7], 0, v[180:181]
	s_add_i32 m0, s48, 0xe000
	s_nop 0
	global_load_lds_dwordx4 v[204:205], off
	s_waitcnt vmcnt(8)
	s_waitcnt lgkmcnt(0)
	s_barrier
	s_setprio 1
	s_waitcnt lgkmcnt(0)
	s_cbranch_vccz .Lb1b_577_0
	ds_read_b128 v[144:147], v213
	ds_read_b128 v[148:151], v213 offset:1024
	ds_read_b128 v[152:155], v213 offset:2048
	ds_read_b128 v[156:159], v213 offset:3072
.Lb1b_577_0:
	v_mfma_f32_16x16x32_bf16 v[124:127], v[128:131], v[160:163], v[124:127]
	v_mfma_f32_16x16x32_bf16 v[120:123], v[136:139], v[160:163], v[120:123]
	v_mfma_f32_16x16x32_bf16 v[108:111], v[128:131], v[188:191], v[108:111]
	v_mfma_f32_16x16x32_bf16 v[104:107], v[136:139], v[188:191], v[104:107]
	v_mfma_f32_16x16x32_bf16 v[92:95], v[128:131], v[196:199], v[92:95]
	v_mfma_f32_16x16x32_bf16 v[88:91], v[136:139], v[196:199], v[88:91]
	v_mfma_f32_16x16x32_bf16 v[76:79], v[128:131], v[216:219], v[76:79]
	v_mfma_f32_16x16x32_bf16 v[72:75], v[136:139], v[216:219], v[72:75]
	v_mfma_f32_16x16x32_bf16 v[124:127], v[132:135], v[184:187], v[124:127]
	v_mfma_f32_16x16x32_bf16 v[120:123], v[140:143], v[184:187], v[120:123]
	v_mfma_f32_16x16x32_bf16 v[108:111], v[132:135], v[192:195], v[108:111]
	v_mfma_f32_16x16x32_bf16 v[104:107], v[140:143], v[192:195], v[104:107]
	v_mfma_f32_16x16x32_bf16 v[92:95], v[132:135], v[200:203], v[92:95]
	v_mfma_f32_16x16x32_bf16 v[88:91], v[140:143], v[200:203], v[88:91]
	v_mfma_f32_16x16x32_bf16 v[76:79], v[132:135], v[220:223], v[76:79]
	v_mfma_f32_16x16x32_bf16 v[72:75], v[140:143], v[220:223], v[72:75]
	s_setprio 0
	s_setprio 1
	s_waitcnt lgkmcnt(0)
	v_mfma_f32_16x16x32_bf16 v[116:119], v[144:147], v[160:163], v[116:119]
	v_mfma_f32_16x16x32_bf16 v[112:115], v[152:155], v[160:163], v[112:115]
	v_mfma_f32_16x16x32_bf16 v[100:103], v[144:147], v[188:191], v[100:103]
	v_mfma_f32_16x16x32_bf16 v[96:99], v[152:155], v[188:191], v[96:99]
	v_mfma_f32_16x16x32_bf16 v[84:87], v[144:147], v[196:199], v[84:87]
	v_mfma_f32_16x16x32_bf16 v[80:83], v[152:155], v[196:199], v[80:83]
	v_mfma_f32_16x16x32_bf16 v[68:71], v[144:147], v[216:219], v[68:71]
	v_mfma_f32_16x16x32_bf16 v[64:67], v[152:155], v[216:219], v[64:67]
	v_mfma_f32_16x16x32_bf16 v[116:119], v[148:151], v[184:187], v[116:119]
	v_mfma_f32_16x16x32_bf16 v[112:115], v[156:159], v[184:187], v[112:115]
	v_mfma_f32_16x16x32_bf16 v[100:103], v[148:151], v[192:195], v[100:103]
	v_mfma_f32_16x16x32_bf16 v[96:99], v[156:159], v[192:195], v[96:99]
	v_mfma_f32_16x16x32_bf16 v[84:87], v[148:151], v[200:203], v[84:87]
	v_mfma_f32_16x16x32_bf16 v[80:83], v[156:159], v[200:203], v[80:83]
	v_mfma_f32_16x16x32_bf16 v[68:71], v[148:151], v[220:223], v[68:71]
	v_mfma_f32_16x16x32_bf16 v[64:67], v[156:159], v[220:223], v[64:67]
	s_setprio 0
	s_barrier
	s_add_i32 s69, s62, s47
	v_lshl_add_u64 v[204:205], s[8:9], 0, v[166:167]
	s_mov_b32 m0, s69
	ds_read_b128 v[160:163], v214 offset:16384
	ds_read_b128 v[184:187], v214 offset:17408
	ds_read_b128 v[188:191], v214 offset:18432
	ds_read_b128 v[192:195], v214 offset:19456
	ds_read_b128 v[196:199], v214 offset:20480
	ds_read_b128 v[200:203], v214 offset:21504
	ds_read_b128 v[216:219], v214 offset:22528
	ds_read_b128 v[220:223], v214 offset:23552
	global_load_lds_dwordx4 v[204:205], off
	s_add_i32 m0, s69, 0x2000
	s_add_u32 s70, s8, 0x100000
	v_lshl_add_u64 v[224:225], s[8:9], 0, v[170:171]
	s_addc_u32 s71, s9, 0
	s_add_i32 s69, s63, s47
	global_load_lds_dwordx4 v[224:225], off
	v_lshl_add_u64 v[226:227], s[70:71], 0, v[166:167]
	s_mov_b32 m0, s69
	v_lshl_add_u64 v[228:229], s[40:41], 0, v[168:169]
	global_load_lds_dwordx4 v[226:227], off
	v_lshl_add_u64 v[226:227], s[70:71], 0, v[170:171]
	s_add_i32 m0, s69, 0x2000
	s_nop 0
	global_load_lds_dwordx4 v[226:227], off
	v_lshl_add_u64 v[226:227], s[40:41], 0, v[164:165]
	s_mov_b32 m0, s48
	s_nop 0
	global_load_lds_dwordx4 v[226:227], off
	s_mov_b32 m0, s49
	s_nop 0
	global_load_lds_dwordx4 v[228:229], off
	s_waitcnt vmcnt(8)
	s_waitcnt lgkmcnt(0)
	s_barrier
; #define PG8_STAGE(bufoff, gbase, voff) do { _Pragma("unroll") for (int _i = 0; _i < 2; ++_i) \
;         __builtin_amdgcn_global_load_lds((const unsigned*)((const char*)(gbase) + (voff)[_i]), (PG8_LAS unsigned*)(lds + (bufoff) + ldsw + _i * 8192), 16, 0, 0); } while (0)
; #define PG8_LDA(dst, b, h) do { _Pragma("unroll") for (int m = 0; m < 4; ++m) _Pragma("unroll") for (int k = 0; k < 2; ++k) dst[m][k] = *(const PG8_LAS bf16x8*)(lds + PG8_SA(b, h) + aoff + m * 2048 + k * 1024); } while (0)
; #define PG8_LDB(dst, b, h) do { _Pragma("unroll") for (int n = 0; n < 2; ++n) _Pragma("unroll") for (int k = 0; k < 2; ++k) dst[n][k] = *(const PG8_LAS bf16x8*)(lds + PG8_SB(b, h) + boff + n * 2048 + k * 1024); } while (0)
; #define PG8_MMA(ai, bj, At, Bt) do { __builtin_amdgcn_s_setprio(1); _Pragma("unroll") for (int m = 0; m < 4; ++m) _Pragma("unroll") for (int n = 0; n < 2; ++n) _Pragma("unroll") for (int k = 0; k < 2; ++k) \
;         acc[ai][bj][m][n] = __builtin_amdgcn_mfma_f32_16x16x32_bf16(Bt[n][k], At[m][k], acc[ai][bj][m][n], 0, 0, 0); __builtin_amdgcn_s_setprio(0); } while (0)
; #define PG8_WAIT_V(n) asm volatile("s_waitcnt vmcnt(" #n ")" ::: "memory")
; #define PG8_WAIT_L(n) asm volatile("s_waitcnt lgkmcnt(" #n ")" ::: "memory")
; #define PG8_BAR __builtin_amdgcn_s_barrier()
; #define PG8_SCHED __builtin_amdgcn_sched_barrier(0)
; template <class Epi, class Sched, bool ALIGN_EPI = false, bool SP2 = false>
; __device__ __forceinline__ void gemm_phase(PG8_LAS unsigned char* lds, const Gemm g, const Sched& S, const Epi& E, int tid_in) {
;     ...
;             PG8_WAIT_V(8); PG8_WAIT_L(0); PG8_BAR; PG8_MMA(1, 0, At, B0); PG8_MMA(1, 1, At, B1); PG8_BAR; PG8_SCHED;
;             PG8_LDB(B0, 1, 0); PG8_LDB(B1, 1, 1); PG8_SCHED; PG8_LDA(At, 1, 0); PG8_STAGE(PG8_SA(0, 1), a2 + hstep, voffA);
;             PG8_WAIT_V(8); PG8_WAIT_L(0); PG8_BAR; PG8_MMA(0, 0, At, B0); PG8_MMA(0, 1, At, B1); PG8_BAR; PG8_SCHED;
	s_setprio 1
	s_waitcnt lgkmcnt(0)
	v_mfma_f32_16x16x32_bf16 v[60:63], v[128:131], v[160:163], v[60:63]
	v_mfma_f32_16x16x32_bf16 v[56:59], v[136:139], v[160:163], v[56:59]
	v_mfma_f32_16x16x32_bf16 v[44:47], v[128:131], v[188:191], v[44:47]
	v_mfma_f32_16x16x32_bf16 v[40:43], v[136:139], v[188:191], v[40:43]
	v_mfma_f32_16x16x32_bf16 v[28:31], v[128:131], v[196:199], v[28:31]
	v_mfma_f32_16x16x32_bf16 v[24:27], v[136:139], v[196:199], v[24:27]
	v_mfma_f32_16x16x32_bf16 v[12:15], v[128:131], v[216:219], v[12:15]
	v_mfma_f32_16x16x32_bf16 v[8:11], v[136:139], v[216:219], v[8:11]
	v_mfma_f32_16x16x32_bf16 v[60:63], v[132:135], v[184:187], v[60:63]
	v_mfma_f32_16x16x32_bf16 v[56:59], v[140:143], v[184:187], v[56:59]
	v_mfma_f32_16x16x32_bf16 v[44:47], v[132:135], v[192:195], v[44:47]
	v_mfma_f32_16x16x32_bf16 v[40:43], v[140:143], v[192:195], v[40:43]
	v_mfma_f32_16x16x32_bf16 v[28:31], v[132:135], v[200:203], v[28:31]
	v_mfma_f32_16x16x32_bf16 v[24:27], v[140:143], v[200:203], v[24:27]
	v_mfma_f32_16x16x32_bf16 v[12:15], v[132:135], v[220:223], v[12:15]
	v_mfma_f32_16x16x32_bf16 v[8:11], v[140:143], v[220:223], v[8:11]
	s_setprio 0
	s_setprio 1
	v_mfma_f32_16x16x32_bf16 v[52:55], v[144:147], v[160:163], v[52:55]
	v_mfma_f32_16x16x32_bf16 v[48:51], v[152:155], v[160:163], v[48:51]
	v_mfma_f32_16x16x32_bf16 v[36:39], v[144:147], v[188:191], v[36:39]
	v_mfma_f32_16x16x32_bf16 v[32:35], v[152:155], v[188:191], v[32:35]
	v_mfma_f32_16x16x32_bf16 v[20:23], v[144:147], v[196:199], v[20:23]
	v_mfma_f32_16x16x32_bf16 v[16:19], v[152:155], v[196:199], v[16:19]
	v_mfma_f32_16x16x32_bf16 v[4:7], v[144:147], v[216:219], v[4:7]
	v_mfma_f32_16x16x32_bf16 v[0:3], v[152:155], v[216:219], v[0:3]
	v_mfma_f32_16x16x32_bf16 v[52:55], v[148:151], v[184:187], v[52:55]
	v_mfma_f32_16x16x32_bf16 v[48:51], v[156:159], v[184:187], v[48:51]
	v_mfma_f32_16x16x32_bf16 v[36:39], v[148:151], v[192:195], v[36:39]
	v_mfma_f32_16x16x32_bf16 v[32:35], v[156:159], v[192:195], v[32:35]
	v_mfma_f32_16x16x32_bf16 v[20:23], v[148:151], v[200:203], v[20:23]
	v_mfma_f32_16x16x32_bf16 v[16:19], v[156:159], v[200:203], v[16:19]
	v_mfma_f32_16x16x32_bf16 v[4:7], v[148:151], v[220:223], v[4:7]
	v_mfma_f32_16x16x32_bf16 v[0:3], v[156:159], v[220:223], v[0:3]
	s_setprio 0
	s_barrier
	s_add_i32 s69, 0, 0x18000
	s_add_i32 s70, 0, 0x1c000
	v_add_u32_e32 v140, s69, v207
	v_add_u32_e32 v156, s70, v207
	ds_read_b128 v[128:131], v140
	ds_read_b128 v[132:135], v140 offset:1024
	ds_read_b128 v[136:139], v140 offset:2048
	ds_read_b128 v[140:143], v140 offset:3072
	s_cbranch_vccnz .Lb1a_577_1
	ds_read_b128 v[144:147], v156
	ds_read_b128 v[148:151], v156 offset:1024
	ds_read_b128 v[152:155], v156 offset:2048
	ds_read_b128 v[156:159], v156 offset:3072
.Lb1a_577_1:
	s_add_u32 s40, s40, 0x100000
	s_addc_u32 s41, s41, 0
	s_mov_b32 m0, s50
	v_lshl_add_u64 v[230:231], s[40:41], 0, v[164:165]
	ds_read_b128 v[160:163], v214 offset:32768
	ds_read_b128 v[184:187], v214 offset:33792
	ds_read_b128 v[188:191], v214 offset:34816
	ds_read_b128 v[192:195], v214 offset:35840
	ds_read_b128 v[196:199], v214 offset:36864
	ds_read_b128 v[200:203], v214 offset:37888
	ds_read_b128 v[216:219], v214 offset:38912
	ds_read_b128 v[220:223], v214 offset:39936
	global_load_lds_dwordx4 v[230:231], off
	v_lshl_add_u64 v[230:231], s[40:41], 0, v[168:169]
	s_mov_b32 m0, s51
	s_nop 0
	global_load_lds_dwordx4 v[230:231], off
	s_waitcnt vmcnt(8)
	s_waitcnt lgkmcnt(0)
	s_barrier
	s_setprio 1
	s_waitcnt lgkmcnt(0)
	s_cbranch_vccz .Lb1b_577_1
	ds_read_b128 v[144:147], v156
	ds_read_b128 v[148:151], v156 offset:1024
	ds_read_b128 v[152:155], v156 offset:2048
	ds_read_b128 v[156:159], v156 offset:3072
; #define PG8_STAGE(bufoff, gbase, voff) do { _Pragma("unroll") for (int _i = 0; _i < 2; ++_i) \
;         __builtin_amdgcn_global_load_lds((const unsigned*)((const char*)(gbase) + (voff)[_i]), (PG8_LAS unsigned*)(lds + (bufoff) + ldsw + _i * 8192), 16, 0, 0); } while (0)
; #define PG8_LDA(dst, b, h) do { _Pragma("unroll") for (int m = 0; m < 4; ++m) _Pragma("unroll") for (int k = 0; k < 2; ++k) dst[m][k] = *(const PG8_LAS bf16x8*)(lds + PG8_SA(b, h) + aoff + m * 2048 + k * 1024); } while (0)
; #define PG8_MMA(ai, bj, At, Bt) do { __builtin_amdgcn_s_setprio(1); _Pragma("unroll") for (int m = 0; m < 4; ++m) _Pragma("unroll") for (int n = 0; n < 2; ++n) _Pragma("unroll") for (int k = 0; k < 2; ++k) \
;         acc[ai][bj][m][n] = __builtin_amdgcn_mfma_f32_16x16x32_bf16(Bt[n][k], At[m][k], acc[ai][bj][m][n], 0, 0, 0); __builtin_amdgcn_s_setprio(0); } while (0)
; #define PG8_WAIT_V(n) asm volatile("s_waitcnt vmcnt(" #n ")" ::: "memory")
; #define PG8_WAIT_L(n) asm volatile("s_waitcnt lgkmcnt(" #n ")" ::: "memory")
; #define PG8_BAR __builtin_amdgcn_s_barrier()
; #define PG8_SCHED __builtin_amdgcn_sched_barrier(0)
; template <class Epi, class Sched, bool ALIGN_EPI = false, bool SP2 = false>
; __device__ __forceinline__ void gemm_phase(PG8_LAS unsigned char* lds, const Gemm g, const Sched& S, const Epi& E, int tid_in) {
;     ...
;         for (int t = 0; t < nt; t += 2) {
;             const bool last = (t == nt - 2);
;     ...
;             PG8_WAIT_V(8); PG8_WAIT_L(0); PG8_BAR; PG8_MMA(0, 0, At, B0); PG8_MMA(0, 1, At, B1); PG8_BAR; PG8_SCHED;
;             PG8_LDA(At, 1, 1); PG8_STAGE(PG8_SB(1, 0), b3, voffB); PG8_STAGE(PG8_SB(1, 1), b3 + hstep, voffB); PG8_STAGE(PG8_SA(1, 0), a3, voffA);
;             PG8_WAIT_V(8); PG8_WAIT_L(0); PG8_BAR; PG8_MMA(1, 0, At, B0); PG8_MMA(1, 1, At, B1); PG8_BAR; PG8_SCHED;
.Lb1b_577_1:
	v_mfma_f32_16x16x32_bf16 v[124:127], v[128:131], v[160:163], v[124:127]
	v_mfma_f32_16x16x32_bf16 v[120:123], v[136:139], v[160:163], v[120:123]
	v_mfma_f32_16x16x32_bf16 v[108:111], v[128:131], v[188:191], v[108:111]
	v_mfma_f32_16x16x32_bf16 v[104:107], v[136:139], v[188:191], v[104:107]
	v_mfma_f32_16x16x32_bf16 v[92:95], v[128:131], v[196:199], v[92:95]
	v_mfma_f32_16x16x32_bf16 v[88:91], v[136:139], v[196:199], v[88:91]
	v_mfma_f32_16x16x32_bf16 v[76:79], v[128:131], v[216:219], v[76:79]
	v_mfma_f32_16x16x32_bf16 v[72:75], v[136:139], v[216:219], v[72:75]
	v_mfma_f32_16x16x32_bf16 v[124:127], v[132:135], v[184:187], v[124:127]
	v_mfma_f32_16x16x32_bf16 v[120:123], v[140:143], v[184:187], v[120:123]
	v_mfma_f32_16x16x32_bf16 v[108:111], v[132:135], v[192:195], v[108:111]
	v_mfma_f32_16x16x32_bf16 v[104:107], v[140:143], v[192:195], v[104:107]
	v_mfma_f32_16x16x32_bf16 v[92:95], v[132:135], v[200:203], v[92:95]
	v_mfma_f32_16x16x32_bf16 v[88:91], v[140:143], v[200:203], v[88:91]
	v_mfma_f32_16x16x32_bf16 v[76:79], v[132:135], v[220:223], v[76:79]
	v_mfma_f32_16x16x32_bf16 v[72:75], v[140:143], v[220:223], v[72:75]
	s_setprio 0
	s_setprio 1
	s_waitcnt lgkmcnt(0)
	v_mfma_f32_16x16x32_bf16 v[116:119], v[144:147], v[160:163], v[116:119]
	v_mfma_f32_16x16x32_bf16 v[112:115], v[152:155], v[160:163], v[112:115]
	v_mfma_f32_16x16x32_bf16 v[100:103], v[144:147], v[188:191], v[100:103]
	v_mfma_f32_16x16x32_bf16 v[96:99], v[152:155], v[188:191], v[96:99]
	v_mfma_f32_16x16x32_bf16 v[84:87], v[144:147], v[196:199], v[84:87]
	v_mfma_f32_16x16x32_bf16 v[80:83], v[152:155], v[196:199], v[80:83]
	v_mfma_f32_16x16x32_bf16 v[68:71], v[144:147], v[216:219], v[68:71]
	v_mfma_f32_16x16x32_bf16 v[64:67], v[152:155], v[216:219], v[64:67]
	v_mfma_f32_16x16x32_bf16 v[116:119], v[148:151], v[184:187], v[116:119]
	v_mfma_f32_16x16x32_bf16 v[112:115], v[156:159], v[184:187], v[112:115]
	v_mfma_f32_16x16x32_bf16 v[100:103], v[148:151], v[192:195], v[100:103]
	v_mfma_f32_16x16x32_bf16 v[96:99], v[156:159], v[192:195], v[96:99]
	v_mfma_f32_16x16x32_bf16 v[84:87], v[148:151], v[200:203], v[84:87]
	v_mfma_f32_16x16x32_bf16 v[80:83], v[156:159], v[200:203], v[80:83]
	v_mfma_f32_16x16x32_bf16 v[68:71], v[148:151], v[220:223], v[68:71]
	v_mfma_f32_16x16x32_bf16 v[64:67], v[156:159], v[220:223], v[64:67]
	s_setprio 0
	s_barrier
	s_add_i32 s40, s69, s47
	v_lshl_add_u64 v[204:205], v[204:205], 0, s[20:21]
	s_mov_b32 m0, s40
	ds_read_b128 v[160:163], v214 offset:49152
	ds_read_b128 v[184:187], v214 offset:50176
	ds_read_b128 v[188:191], v214 offset:51200
	ds_read_b128 v[192:195], v214 offset:52224
	ds_read_b128 v[196:199], v214 offset:53248
	ds_read_b128 v[200:203], v214 offset:54272
	ds_read_b128 v[216:219], v214 offset:55296
	ds_read_b128 v[220:223], v214 offset:56320
	global_load_lds_dwordx4 v[204:205], off
	s_add_i32 m0, s40, 0x2000
	s_add_u32 s8, s8, 0x100080
	v_lshl_add_u64 v[204:205], v[224:225], 0, s[20:21]
	s_addc_u32 s9, s9, 0
	s_add_i32 s40, s70, s47
	global_load_lds_dwordx4 v[204:205], off
	v_lshl_add_u64 v[204:205], s[8:9], 0, v[166:167]
	s_mov_b32 m0, s40
	s_nop 0
	global_load_lds_dwordx4 v[204:205], off
	v_lshl_add_u64 v[204:205], s[8:9], 0, v[170:171]
	s_add_i32 m0, s40, 0x2000
	s_nop 0
	global_load_lds_dwordx4 v[204:205], off
	v_lshl_add_u64 v[204:205], v[226:227], 0, s[20:21]
	s_mov_b32 m0, s58
	s_nop 0
	global_load_lds_dwordx4 v[204:205], off
	v_lshl_add_u64 v[204:205], v[228:229], 0, s[20:21]
	s_mov_b32 m0, s59
	s_nop 0
	global_load_lds_dwordx4 v[204:205], off
	s_waitcnt vmcnt(8)
	s_waitcnt lgkmcnt(0)
	s_barrier
	s_setprio 1
	s_waitcnt lgkmcnt(0)
	v_mfma_f32_16x16x32_bf16 v[60:63], v[128:131], v[160:163], v[60:63]
	v_mfma_f32_16x16x32_bf16 v[56:59], v[136:139], v[160:163], v[56:59]
	v_mfma_f32_16x16x32_bf16 v[44:47], v[128:131], v[188:191], v[44:47]
	v_mfma_f32_16x16x32_bf16 v[40:43], v[136:139], v[188:191], v[40:43]
	v_mfma_f32_16x16x32_bf16 v[28:31], v[128:131], v[196:199], v[28:31]
	v_mfma_f32_16x16x32_bf16 v[24:27], v[136:139], v[196:199], v[24:27]
	v_mfma_f32_16x16x32_bf16 v[12:15], v[128:131], v[216:219], v[12:15]
	v_mfma_f32_16x16x32_bf16 v[8:11], v[136:139], v[216:219], v[8:11]
	v_mfma_f32_16x16x32_bf16 v[60:63], v[132:135], v[184:187], v[60:63]
	v_mfma_f32_16x16x32_bf16 v[56:59], v[140:143], v[184:187], v[56:59]
	v_mfma_f32_16x16x32_bf16 v[44:47], v[132:135], v[192:195], v[44:47]
	v_mfma_f32_16x16x32_bf16 v[40:43], v[140:143], v[192:195], v[40:43]
	v_mfma_f32_16x16x32_bf16 v[28:31], v[132:135], v[200:203], v[28:31]
	v_mfma_f32_16x16x32_bf16 v[24:27], v[140:143], v[200:203], v[24:27]
	v_mfma_f32_16x16x32_bf16 v[12:15], v[132:135], v[220:223], v[12:15]
	v_mfma_f32_16x16x32_bf16 v[8:11], v[140:143], v[220:223], v[8:11]
	s_setprio 0
	s_setprio 1
	v_mfma_f32_16x16x32_bf16 v[52:55], v[144:147], v[160:163], v[52:55]
	v_mfma_f32_16x16x32_bf16 v[48:51], v[152:155], v[160:163], v[48:51]
	v_mfma_f32_16x16x32_bf16 v[36:39], v[144:147], v[188:191], v[36:39]
	v_mfma_f32_16x16x32_bf16 v[32:35], v[152:155], v[188:191], v[32:35]
	v_mfma_f32_16x16x32_bf16 v[20:23], v[144:147], v[196:199], v[20:23]
	v_mfma_f32_16x16x32_bf16 v[16:19], v[152:155], v[196:199], v[16:19]
	v_mfma_f32_16x16x32_bf16 v[4:7], v[144:147], v[216:219], v[4:7]
	v_mfma_f32_16x16x32_bf16 v[0:3], v[152:155], v[216:219], v[0:3]
	v_mfma_f32_16x16x32_bf16 v[52:55], v[148:151], v[184:187], v[52:55]
	v_mfma_f32_16x16x32_bf16 v[48:51], v[156:159], v[184:187], v[48:51]
	v_mfma_f32_16x16x32_bf16 v[36:39], v[148:151], v[192:195], v[36:39]
	v_mfma_f32_16x16x32_bf16 v[32:35], v[156:159], v[192:195], v[32:35]
	v_mfma_f32_16x16x32_bf16 v[20:23], v[148:151], v[200:203], v[20:23]
	v_mfma_f32_16x16x32_bf16 v[16:19], v[156:159], v[200:203], v[16:19]
	v_mfma_f32_16x16x32_bf16 v[4:7], v[148:151], v[220:223], v[4:7]
	v_mfma_f32_16x16x32_bf16 v[0:3], v[156:159], v[220:223], v[0:3]
	s_setprio 0
	s_barrier
	s_add_i32 s43, s43, 2
	s_add_u32 s6, s6, 0x100
	s_addc_u32 s7, s7, 0
	s_add_u32 s31, s31, 0x100
	s_addc_u32 s42, s42, 0
	s_cmp_gt_u32 s43, 61
	s_cbranch_scc0 .LBB0_577
	s_and_b64 vcc, exec, s[22:23]
	s_cbranch_vccnz .LBB0_581
	v_lshl_add_u32 v184, s4, 8, v206
	s_cmp_gt_i32 s0, 15
	s_mov_b64 s[4:5], -1
	s_cbranch_scc1 .LBB0_582

; #define PG8_STAGE(bufoff, gbase, voff) do { _Pragma("unroll") for (int _i = 0; _i < 2; ++_i) \
;         __builtin_amdgcn_global_load_lds((const unsigned*)((const char*)(gbase) + (voff)[_i]), (PG8_LAS unsigned*)(lds + (bufoff) + ldsw + _i * 8192), 16, 0, 0); } while (0)
; #define PG8_LDA(dst, b, h) do { _Pragma("unroll") for (int m = 0; m < 4; ++m) _Pragma("unroll") for (int k = 0; k < 2; ++k) dst[m][k] = *(const PG8_LAS bf16x8*)(lds + PG8_SA(b, h) + aoff + m * 2048 + k * 1024); } while (0)
; #define PG8_LDB(dst, b, h) do { _Pragma("unroll") for (int n = 0; n < 2; ++n) _Pragma("unroll") for (int k = 0; k < 2; ++k) dst[n][k] = *(const PG8_LAS bf16x8*)(lds + PG8_SB(b, h) + boff + n * 2048 + k * 1024); } while (0)
; #define PG8_MMA(ai, bj, At, Bt) do { __builtin_amdgcn_s_setprio(1); _Pragma("unroll") for (int m = 0; m < 4; ++m) _Pragma("unroll") for (int n = 0; n < 2; ++n) _Pragma("unroll") for (int k = 0; k < 2; ++k) \
;         acc[ai][bj][m][n] = __builtin_amdgcn_mfma_f32_16x16x32_bf16(Bt[n][k], At[m][k], acc[ai][bj][m][n], 0, 0, 0); __builtin_amdgcn_s_setprio(0); } while (0)
; #define PG8_WAIT_V(n) asm volatile("s_waitcnt vmcnt(" #n ")" ::: "memory")
; #define PG8_WAIT_L(n) asm volatile("s_waitcnt lgkmcnt(" #n ")" ::: "memory")
; template <class Epi, class Sched, bool ALIGN_EPI = false, bool SP2 = false>
; __device__ __forceinline__ void gemm_phase(PG8_LAS unsigned char* lds, const Gemm g, const Sched& S, const Epi& E, int tid_in) {
;     ...
;             const bool last = (t == nt - 2);
;             const char* a1 = cA + (size_t)(t + 1) * kstep;
;             const char* a2 = last ? nA : cA + (size_t)(t + 2) * kstep; const char* b2 = last ? nB : cB + (size_t)(t + 2) * kstep;
;             const char* a3 = a2 + kstep; const char* b3 = b2 + kstep;
;             if (last && has_next) S.a_ready(nxt);
;             if constexpr (SP2) {
;             PG8_LDB(B0, 0, 0); PG8_LDB(B1, 0, 1); PG8_SCHED; PG8_LDA(At, 0, 0); PG8_STAGE(PG8_SA(1, 1), a1 + hstep, voffA);
;             PG8_WAIT_V(8); PG8_WAIT_L(0); PG8_BAR; PG8_MMA(0, 0, At, B0); PG8_MMA(0, 1, At, B1); PG8_BAR; PG8_SCHED;
;             PG8_LDA(At, 0, 1); PG8_STAGE(PG8_SB(0, 0), b2, voffB); PG8_STAGE(PG8_SB(0, 1), b2 + hstep, voffB); PG8_STAGE(PG8_SA(0, 0), a2, voffA);
;             PG8_WAIT_V(8); PG8_WAIT_L(0); PG8_BAR; PG8_MMA(1, 0, At, B0); PG8_MMA(1, 1, At, B1); PG8_BAR; PG8_SCHED;
.LBB0_1369:
	s_mov_b64 vcc, s[8:9]
	ds_read_b128 v[144:147], v153
	ds_read_b128 v[156:159], v153 offset:1024
	ds_read_b128 v[160:163], v153 offset:2048
	ds_read_b128 v[164:167], v153 offset:3072
	s_cbranch_vccnz .Lb1a_1369_0
	ds_read_b128 v[168:171], v154
	ds_read_b128 v[172:175], v154 offset:1024
	ds_read_b128 v[176:179], v154 offset:2048
	ds_read_b128 v[180:183], v154 offset:3072
.Lb1a_1369_0:
	s_add_u32 s28, s26, 0xfff00080
	s_addc_u32 s29, s27, -1
	s_cmp_eq_u32 s54, 60
	s_cselect_b32 s31, s2, s29
	s_cselect_b32 s30, s15, s28
	s_cselect_b32 s29, s13, s53
	s_cselect_b32 s28, s23, s25
	v_lshl_add_u64 v[148:149], s[26:27], 0, v[138:139]
	s_add_i32 m0, s37, 0xc000
	ds_read_b128 v[184:187], v155
	ds_read_b128 v[188:191], v155 offset:1024
	ds_read_b128 v[192:195], v155 offset:2048
	ds_read_b128 v[196:199], v155 offset:3072
	ds_read_b128 v[200:203], v155 offset:4096
	ds_read_b128 v[204:207], v155 offset:5120
	ds_read_b128 v[208:211], v155 offset:6144
	ds_read_b128 v[212:215], v155 offset:7168
	global_load_lds_dwordx4 v[148:149], off
	v_lshl_add_u64 v[148:149], s[26:27], 0, v[140:141]
	s_add_i32 m0, s37, 0xe000
	s_nop 0
	global_load_lds_dwordx4 v[148:149], off
	s_waitcnt vmcnt(8)
	s_waitcnt lgkmcnt(0)
	s_barrier
	s_setprio 1
	s_waitcnt lgkmcnt(0)
	s_cbranch_vccz .Lb1b_1369_0
	ds_read_b128 v[168:171], v154
	ds_read_b128 v[172:175], v154 offset:1024
	ds_read_b128 v[176:179], v154 offset:2048
	ds_read_b128 v[180:183], v154 offset:3072
.Lb1b_1369_0:
	v_mfma_f32_16x16x32_bf16 v[124:127], v[144:147], v[184:187], v[124:127]
	v_mfma_f32_16x16x32_bf16 v[120:123], v[160:163], v[184:187], v[120:123]
	v_mfma_f32_16x16x32_bf16 v[108:111], v[144:147], v[192:195], v[108:111]
	v_mfma_f32_16x16x32_bf16 v[104:107], v[160:163], v[192:195], v[104:107]
	v_mfma_f32_16x16x32_bf16 v[92:95], v[144:147], v[200:203], v[92:95]
	v_mfma_f32_16x16x32_bf16 v[88:91], v[160:163], v[200:203], v[88:91]
	v_mfma_f32_16x16x32_bf16 v[76:79], v[144:147], v[208:211], v[76:79]
	v_mfma_f32_16x16x32_bf16 v[72:75], v[160:163], v[208:211], v[72:75]
	v_mfma_f32_16x16x32_bf16 v[124:127], v[156:159], v[188:191], v[124:127]
	v_mfma_f32_16x16x32_bf16 v[120:123], v[164:167], v[188:191], v[120:123]
	v_mfma_f32_16x16x32_bf16 v[108:111], v[156:159], v[196:199], v[108:111]
	v_mfma_f32_16x16x32_bf16 v[104:107], v[164:167], v[196:199], v[104:107]
	v_mfma_f32_16x16x32_bf16 v[92:95], v[156:159], v[204:207], v[92:95]
	v_mfma_f32_16x16x32_bf16 v[88:91], v[164:167], v[204:207], v[88:91]
	v_mfma_f32_16x16x32_bf16 v[76:79], v[156:159], v[212:215], v[76:79]
	v_mfma_f32_16x16x32_bf16 v[72:75], v[164:167], v[212:215], v[72:75]
	s_setprio 0
	s_setprio 1
	s_waitcnt lgkmcnt(0)
	v_mfma_f32_16x16x32_bf16 v[116:119], v[168:171], v[184:187], v[116:119]
	v_mfma_f32_16x16x32_bf16 v[112:115], v[176:179], v[184:187], v[112:115]
	v_mfma_f32_16x16x32_bf16 v[100:103], v[168:171], v[192:195], v[100:103]
	v_mfma_f32_16x16x32_bf16 v[96:99], v[176:179], v[192:195], v[96:99]
	v_mfma_f32_16x16x32_bf16 v[84:87], v[168:171], v[200:203], v[84:87]
	v_mfma_f32_16x16x32_bf16 v[80:83], v[176:179], v[200:203], v[80:83]
	v_mfma_f32_16x16x32_bf16 v[68:71], v[168:171], v[208:211], v[68:71]
	v_mfma_f32_16x16x32_bf16 v[64:67], v[176:179], v[208:211], v[64:67]
	v_mfma_f32_16x16x32_bf16 v[116:119], v[172:175], v[188:191], v[116:119]
	v_mfma_f32_16x16x32_bf16 v[112:115], v[180:183], v[188:191], v[112:115]
	v_mfma_f32_16x16x32_bf16 v[100:103], v[172:175], v[196:199], v[100:103]
	v_mfma_f32_16x16x32_bf16 v[96:99], v[180:183], v[196:199], v[96:99]
	v_mfma_f32_16x16x32_bf16 v[84:87], v[172:175], v[204:207], v[84:87]
	v_mfma_f32_16x16x32_bf16 v[80:83], v[180:183], v[204:207], v[80:83]
	v_mfma_f32_16x16x32_bf16 v[68:71], v[172:175], v[212:215], v[68:71]
	v_mfma_f32_16x16x32_bf16 v[64:67], v[180:183], v[212:215], v[64:67]
	s_setprio 0
	s_barrier
	s_add_i32 s55, s46, s36
	v_lshl_add_u64 v[148:149], s[28:29], 0, v[130:131]
	s_mov_b32 m0, s55
	ds_read_b128 v[184:187], v155 offset:16384
	ds_read_b128 v[188:191], v155 offset:17408
	ds_read_b128 v[192:195], v155 offset:18432
	ds_read_b128 v[196:199], v155 offset:19456
	ds_read_b128 v[200:203], v155 offset:20480
	ds_read_b128 v[204:207], v155 offset:21504
	ds_read_b128 v[208:211], v155 offset:22528
	ds_read_b128 v[212:215], v155 offset:23552
	global_load_lds_dwordx4 v[148:149], off
	s_add_i32 m0, s55, 0x2000
	s_add_u32 s56, s28, 0x100000
	v_lshl_add_u64 v[216:217], s[28:29], 0, v[134:135]
	s_addc_u32 s57, s29, 0
	s_add_i32 s55, s47, s36
	global_load_lds_dwordx4 v[216:217], off
	v_lshl_add_u64 v[218:219], s[56:57], 0, v[130:131]
	s_mov_b32 m0, s55
	v_lshl_add_u64 v[220:221], s[30:31], 0, v[132:133]
	global_load_lds_dwordx4 v[218:219], off
	v_lshl_add_u64 v[218:219], s[56:57], 0, v[134:135]
	s_add_i32 m0, s55, 0x2000
	s_nop 0
	global_load_lds_dwordx4 v[218:219], off
	v_lshl_add_u64 v[218:219], s[30:31], 0, v[128:129]
	s_mov_b32 m0, s37
	s_nop 0
	global_load_lds_dwordx4 v[218:219], off
	s_mov_b32 m0, s38
	s_nop 0
	global_load_lds_dwordx4 v[220:221], off
	s_waitcnt vmcnt(8)
	s_waitcnt lgkmcnt(0)
	s_barrier
; #define PG8_STAGE(bufoff, gbase, voff) do { _Pragma("unroll") for (int _i = 0; _i < 2; ++_i) \
;         __builtin_amdgcn_global_load_lds((const unsigned*)((const char*)(gbase) + (voff)[_i]), (PG8_LAS unsigned*)(lds + (bufoff) + ldsw + _i * 8192), 16, 0, 0); } while (0)
; #define PG8_LDA(dst, b, h) do { _Pragma("unroll") for (int m = 0; m < 4; ++m) _Pragma("unroll") for (int k = 0; k < 2; ++k) dst[m][k] = *(const PG8_LAS bf16x8*)(lds + PG8_SA(b, h) + aoff + m * 2048 + k * 1024); } while (0)
; #define PG8_LDB(dst, b, h) do { _Pragma("unroll") for (int n = 0; n < 2; ++n) _Pragma("unroll") for (int k = 0; k < 2; ++k) dst[n][k] = *(const PG8_LAS bf16x8*)(lds + PG8_SB(b, h) + boff + n * 2048 + k * 1024); } while (0)
; #define PG8_MMA(ai, bj, At, Bt) do { __builtin_amdgcn_s_setprio(1); _Pragma("unroll") for (int m = 0; m < 4; ++m) _Pragma("unroll") for (int n = 0; n < 2; ++n) _Pragma("unroll") for (int k = 0; k < 2; ++k) \
;         acc[ai][bj][m][n] = __builtin_amdgcn_mfma_f32_16x16x32_bf16(Bt[n][k], At[m][k], acc[ai][bj][m][n], 0, 0, 0); __builtin_amdgcn_s_setprio(0); } while (0)
; #define PG8_WAIT_V(n) asm volatile("s_waitcnt vmcnt(" #n ")" ::: "memory")
; #define PG8_WAIT_L(n) asm volatile("s_waitcnt lgkmcnt(" #n ")" ::: "memory")
; #define PG8_BAR __builtin_amdgcn_s_barrier()
; #define PG8_SCHED __builtin_amdgcn_sched_barrier(0)
; template <class Epi, class Sched, bool ALIGN_EPI = false, bool SP2 = false>
; __device__ __forceinline__ void gemm_phase(PG8_LAS unsigned char* lds, const Gemm g, const Sched& S, const Epi& E, int tid_in) {
;     ...
;             PG8_WAIT_V(8); PG8_WAIT_L(0); PG8_BAR; PG8_MMA(1, 0, At, B0); PG8_MMA(1, 1, At, B1); PG8_BAR; PG8_SCHED;
;             PG8_LDB(B0, 1, 0); PG8_LDB(B1, 1, 1); PG8_SCHED; PG8_LDA(At, 1, 0); PG8_STAGE(PG8_SA(0, 1), a2 + hstep, voffA);
;             PG8_WAIT_V(8); PG8_WAIT_L(0); PG8_BAR; PG8_MMA(0, 0, At, B0); PG8_MMA(0, 1, At, B1); PG8_BAR; PG8_SCHED;
	s_setprio 1
	s_waitcnt lgkmcnt(0)
	v_mfma_f32_16x16x32_bf16 v[60:63], v[144:147], v[184:187], v[60:63]
	v_mfma_f32_16x16x32_bf16 v[56:59], v[160:163], v[184:187], v[56:59]
	v_mfma_f32_16x16x32_bf16 v[44:47], v[144:147], v[192:195], v[44:47]
	v_mfma_f32_16x16x32_bf16 v[40:43], v[160:163], v[192:195], v[40:43]
	v_mfma_f32_16x16x32_bf16 v[28:31], v[144:147], v[200:203], v[28:31]
	v_mfma_f32_16x16x32_bf16 v[24:27], v[160:163], v[200:203], v[24:27]
	v_mfma_f32_16x16x32_bf16 v[12:15], v[144:147], v[208:211], v[12:15]
	v_mfma_f32_16x16x32_bf16 v[8:11], v[160:163], v[208:211], v[8:11]
	v_mfma_f32_16x16x32_bf16 v[60:63], v[156:159], v[188:191], v[60:63]
	v_mfma_f32_16x16x32_bf16 v[56:59], v[164:167], v[188:191], v[56:59]
	v_mfma_f32_16x16x32_bf16 v[44:47], v[156:159], v[196:199], v[44:47]
	v_mfma_f32_16x16x32_bf16 v[40:43], v[164:167], v[196:199], v[40:43]
	v_mfma_f32_16x16x32_bf16 v[28:31], v[156:159], v[204:207], v[28:31]
	v_mfma_f32_16x16x32_bf16 v[24:27], v[164:167], v[204:207], v[24:27]
	v_mfma_f32_16x16x32_bf16 v[12:15], v[156:159], v[212:215], v[12:15]
	v_mfma_f32_16x16x32_bf16 v[8:11], v[164:167], v[212:215], v[8:11]
	s_setprio 0
	s_setprio 1
	v_mfma_f32_16x16x32_bf16 v[52:55], v[168:171], v[184:187], v[52:55]
	v_mfma_f32_16x16x32_bf16 v[48:51], v[176:179], v[184:187], v[48:51]
	v_mfma_f32_16x16x32_bf16 v[36:39], v[168:171], v[192:195], v[36:39]
	v_mfma_f32_16x16x32_bf16 v[32:35], v[176:179], v[192:195], v[32:35]
	v_mfma_f32_16x16x32_bf16 v[20:23], v[168:171], v[200:203], v[20:23]
	v_mfma_f32_16x16x32_bf16 v[16:19], v[176:179], v[200:203], v[16:19]
	v_mfma_f32_16x16x32_bf16 v[4:7], v[168:171], v[208:211], v[4:7]
	v_mfma_f32_16x16x32_bf16 v[0:3], v[176:179], v[208:211], v[0:3]
	v_mfma_f32_16x16x32_bf16 v[52:55], v[172:175], v[188:191], v[52:55]
	v_mfma_f32_16x16x32_bf16 v[48:51], v[180:183], v[188:191], v[48:51]
	v_mfma_f32_16x16x32_bf16 v[36:39], v[172:175], v[196:199], v[36:39]
	v_mfma_f32_16x16x32_bf16 v[32:35], v[180:183], v[196:199], v[32:35]
	v_mfma_f32_16x16x32_bf16 v[20:23], v[172:175], v[204:207], v[20:23]
	v_mfma_f32_16x16x32_bf16 v[16:19], v[180:183], v[204:207], v[16:19]
	v_mfma_f32_16x16x32_bf16 v[4:7], v[172:175], v[212:215], v[4:7]
	v_mfma_f32_16x16x32_bf16 v[0:3], v[180:183], v[212:215], v[0:3]
	s_setprio 0
	s_barrier
	s_add_i32 s55, 0, 0x18000
	v_add_u32_e32 v136, s55, v151
	s_add_i32 s56, 0, 0x1c000
	ds_read_b128 v[144:147], v136
	ds_read_b128 v[156:159], v136 offset:1024
	ds_read_b128 v[160:163], v136 offset:2048
	ds_read_b128 v[164:167], v136 offset:3072
	v_add_u32_e32 v136, s56, v151
	s_cbranch_vccnz .Lb1a_1369_1
	ds_read_b128 v[168:171], v136
	ds_read_b128 v[172:175], v136 offset:1024
	ds_read_b128 v[176:179], v136 offset:2048
	ds_read_b128 v[180:183], v136 offset:3072
.Lb1a_1369_1:
	s_add_u32 s30, s30, 0x100000
	s_addc_u32 s31, s31, 0
	s_mov_b32 m0, s39
	v_lshl_add_u64 v[222:223], s[30:31], 0, v[128:129]
	ds_read_b128 v[184:187], v155 offset:32768
	ds_read_b128 v[188:191], v155 offset:33792
	ds_read_b128 v[192:195], v155 offset:34816
	ds_read_b128 v[196:199], v155 offset:35840
	ds_read_b128 v[200:203], v155 offset:36864
	ds_read_b128 v[204:207], v155 offset:37888
	ds_read_b128 v[208:211], v155 offset:38912
	ds_read_b128 v[212:215], v155 offset:39936
	global_load_lds_dwordx4 v[222:223], off
	v_lshl_add_u64 v[222:223], s[30:31], 0, v[132:133]
	s_mov_b32 m0, s40
	s_nop 0
	global_load_lds_dwordx4 v[222:223], off
	s_waitcnt vmcnt(8)
	s_waitcnt lgkmcnt(0)
	s_barrier
	s_setprio 1
	s_waitcnt lgkmcnt(0)
	s_cbranch_vccz .Lb1b_1369_1
	ds_read_b128 v[168:171], v136
	ds_read_b128 v[172:175], v136 offset:1024
	ds_read_b128 v[176:179], v136 offset:2048
	ds_read_b128 v[180:183], v136 offset:3072
; #define PG8_STAGE(bufoff, gbase, voff) do { _Pragma("unroll") for (int _i = 0; _i < 2; ++_i) \
;         __builtin_amdgcn_global_load_lds((const unsigned*)((const char*)(gbase) + (voff)[_i]), (PG8_LAS unsigned*)(lds + (bufoff) + ldsw + _i * 8192), 16, 0, 0); } while (0)
; #define PG8_LDA(dst, b, h) do { _Pragma("unroll") for (int m = 0; m < 4; ++m) _Pragma("unroll") for (int k = 0; k < 2; ++k) dst[m][k] = *(const PG8_LAS bf16x8*)(lds + PG8_SA(b, h) + aoff + m * 2048 + k * 1024); } while (0)
; #define PG8_MMA(ai, bj, At, Bt) do { __builtin_amdgcn_s_setprio(1); _Pragma("unroll") for (int m = 0; m < 4; ++m) _Pragma("unroll") for (int n = 0; n < 2; ++n) _Pragma("unroll") for (int k = 0; k < 2; ++k) \
;         acc[ai][bj][m][n] = __builtin_amdgcn_mfma_f32_16x16x32_bf16(Bt[n][k], At[m][k], acc[ai][bj][m][n], 0, 0, 0); __builtin_amdgcn_s_setprio(0); } while (0)
; #define PG8_WAIT_V(n) asm volatile("s_waitcnt vmcnt(" #n ")" ::: "memory")
; #define PG8_WAIT_L(n) asm volatile("s_waitcnt lgkmcnt(" #n ")" ::: "memory")
; #define PG8_BAR __builtin_amdgcn_s_barrier()
; #define PG8_SCHED __builtin_amdgcn_sched_barrier(0)
; template <class Epi, class Sched, bool ALIGN_EPI = false, bool SP2 = false>
; __device__ __forceinline__ void gemm_phase(PG8_LAS unsigned char* lds, const Gemm g, const Sched& S, const Epi& E, int tid_in) {
;     ...
;             PG8_WAIT_V(8); PG8_WAIT_L(0); PG8_BAR; PG8_MMA(0, 0, At, B0); PG8_MMA(0, 1, At, B1); PG8_BAR; PG8_SCHED;
;             PG8_LDA(At, 1, 1); PG8_STAGE(PG8_SB(1, 0), b3, voffB); PG8_STAGE(PG8_SB(1, 1), b3 + hstep, voffB); PG8_STAGE(PG8_SA(1, 0), a3, voffA);
;             PG8_WAIT_V(8); PG8_WAIT_L(0); PG8_BAR; PG8_MMA(1, 0, At, B0); PG8_MMA(1, 1, At, B1); PG8_BAR; PG8_SCHED;
;     ...
;         if constexpr (ALIGN_EPI) { if (wr == 0) PG8_BAR; }
.Lb1b_1369_1:
	v_mfma_f32_16x16x32_bf16 v[124:127], v[144:147], v[184:187], v[124:127]
	v_mfma_f32_16x16x32_bf16 v[120:123], v[160:163], v[184:187], v[120:123]
	v_mfma_f32_16x16x32_bf16 v[108:111], v[144:147], v[192:195], v[108:111]
	v_mfma_f32_16x16x32_bf16 v[104:107], v[160:163], v[192:195], v[104:107]
	v_mfma_f32_16x16x32_bf16 v[92:95], v[144:147], v[200:203], v[92:95]
	v_mfma_f32_16x16x32_bf16 v[88:91], v[160:163], v[200:203], v[88:91]
	v_mfma_f32_16x16x32_bf16 v[76:79], v[144:147], v[208:211], v[76:79]
	v_mfma_f32_16x16x32_bf16 v[72:75], v[160:163], v[208:211], v[72:75]
	v_mfma_f32_16x16x32_bf16 v[124:127], v[156:159], v[188:191], v[124:127]
	v_mfma_f32_16x16x32_bf16 v[120:123], v[164:167], v[188:191], v[120:123]
	v_mfma_f32_16x16x32_bf16 v[108:111], v[156:159], v[196:199], v[108:111]
	v_mfma_f32_16x16x32_bf16 v[104:107], v[164:167], v[196:199], v[104:107]
	v_mfma_f32_16x16x32_bf16 v[92:95], v[156:159], v[204:207], v[92:95]
	v_mfma_f32_16x16x32_bf16 v[88:91], v[164:167], v[204:207], v[88:91]
	v_mfma_f32_16x16x32_bf16 v[76:79], v[156:159], v[212:215], v[76:79]
	v_mfma_f32_16x16x32_bf16 v[72:75], v[164:167], v[212:215], v[72:75]
	s_setprio 0
	s_setprio 1
	s_waitcnt lgkmcnt(0)
	v_mfma_f32_16x16x32_bf16 v[116:119], v[168:171], v[184:187], v[116:119]
	v_mfma_f32_16x16x32_bf16 v[112:115], v[176:179], v[184:187], v[112:115]
	v_mfma_f32_16x16x32_bf16 v[100:103], v[168:171], v[192:195], v[100:103]
	v_mfma_f32_16x16x32_bf16 v[96:99], v[176:179], v[192:195], v[96:99]
	v_mfma_f32_16x16x32_bf16 v[84:87], v[168:171], v[200:203], v[84:87]
	v_mfma_f32_16x16x32_bf16 v[80:83], v[176:179], v[200:203], v[80:83]
	v_mfma_f32_16x16x32_bf16 v[68:71], v[168:171], v[208:211], v[68:71]
	v_mfma_f32_16x16x32_bf16 v[64:67], v[176:179], v[208:211], v[64:67]
	v_mfma_f32_16x16x32_bf16 v[116:119], v[172:175], v[188:191], v[116:119]
	v_mfma_f32_16x16x32_bf16 v[112:115], v[180:183], v[188:191], v[112:115]
	v_mfma_f32_16x16x32_bf16 v[100:103], v[172:175], v[196:199], v[100:103]
	v_mfma_f32_16x16x32_bf16 v[96:99], v[180:183], v[196:199], v[96:99]
	v_mfma_f32_16x16x32_bf16 v[84:87], v[172:175], v[204:207], v[84:87]
	v_mfma_f32_16x16x32_bf16 v[80:83], v[180:183], v[204:207], v[80:83]
	v_mfma_f32_16x16x32_bf16 v[68:71], v[172:175], v[212:215], v[68:71]
	v_mfma_f32_16x16x32_bf16 v[64:67], v[180:183], v[212:215], v[64:67]
	s_setprio 0
	s_barrier
	s_add_i32 s30, s55, s36
	v_lshl_add_u64 v[148:149], v[148:149], 0, s[6:7]
	s_mov_b32 m0, s30
	ds_read_b128 v[184:187], v155 offset:49152
	ds_read_b128 v[188:191], v155 offset:50176
	ds_read_b128 v[192:195], v155 offset:51200
	ds_read_b128 v[196:199], v155 offset:52224
	ds_read_b128 v[200:203], v155 offset:53248
	ds_read_b128 v[204:207], v155 offset:54272
	ds_read_b128 v[208:211], v155 offset:55296
	ds_read_b128 v[212:215], v155 offset:56320
	global_load_lds_dwordx4 v[148:149], off
	s_add_i32 m0, s30, 0x2000
	s_add_u32 s28, s28, 0x100080
	v_lshl_add_u64 v[148:149], v[216:217], 0, s[6:7]
	s_addc_u32 s29, s29, 0
	s_add_i32 s30, s56, s36
	global_load_lds_dwordx4 v[148:149], off
	v_lshl_add_u64 v[148:149], s[28:29], 0, v[130:131]
	s_mov_b32 m0, s30
	s_nop 0
	global_load_lds_dwordx4 v[148:149], off
	v_lshl_add_u64 v[148:149], s[28:29], 0, v[134:135]
	s_add_i32 m0, s30, 0x2000
	s_nop 0
	global_load_lds_dwordx4 v[148:149], off
	v_lshl_add_u64 v[148:149], v[218:219], 0, s[6:7]
	s_mov_b32 m0, s42
	s_nop 0
	global_load_lds_dwordx4 v[148:149], off
	v_lshl_add_u64 v[148:149], v[220:221], 0, s[6:7]
	s_mov_b32 m0, s44
	s_nop 0
	global_load_lds_dwordx4 v[148:149], off
	s_waitcnt vmcnt(8)
	s_waitcnt lgkmcnt(0)
	s_barrier
	s_setprio 1
	s_waitcnt lgkmcnt(0)
	v_mfma_f32_16x16x32_bf16 v[60:63], v[144:147], v[184:187], v[60:63]
	v_mfma_f32_16x16x32_bf16 v[56:59], v[160:163], v[184:187], v[56:59]
	v_mfma_f32_16x16x32_bf16 v[44:47], v[144:147], v[192:195], v[44:47]
	v_mfma_f32_16x16x32_bf16 v[40:43], v[160:163], v[192:195], v[40:43]
	v_mfma_f32_16x16x32_bf16 v[28:31], v[144:147], v[200:203], v[28:31]
	v_mfma_f32_16x16x32_bf16 v[24:27], v[160:163], v[200:203], v[24:27]
	v_mfma_f32_16x16x32_bf16 v[12:15], v[144:147], v[208:211], v[12:15]
	v_mfma_f32_16x16x32_bf16 v[8:11], v[160:163], v[208:211], v[8:11]
	v_mfma_f32_16x16x32_bf16 v[60:63], v[156:159], v[188:191], v[60:63]
	v_mfma_f32_16x16x32_bf16 v[56:59], v[164:167], v[188:191], v[56:59]
	v_mfma_f32_16x16x32_bf16 v[44:47], v[156:159], v[196:199], v[44:47]
	v_mfma_f32_16x16x32_bf16 v[40:43], v[164:167], v[196:199], v[40:43]
	v_mfma_f32_16x16x32_bf16 v[28:31], v[156:159], v[204:207], v[28:31]
	v_mfma_f32_16x16x32_bf16 v[24:27], v[164:167], v[204:207], v[24:27]
	v_mfma_f32_16x16x32_bf16 v[12:15], v[156:159], v[212:215], v[12:15]
	v_mfma_f32_16x16x32_bf16 v[8:11], v[164:167], v[212:215], v[8:11]
	s_setprio 0
	s_setprio 1
	v_mfma_f32_16x16x32_bf16 v[52:55], v[168:171], v[184:187], v[52:55]
	v_mfma_f32_16x16x32_bf16 v[48:51], v[176:179], v[184:187], v[48:51]
	v_mfma_f32_16x16x32_bf16 v[36:39], v[168:171], v[192:195], v[36:39]
	v_mfma_f32_16x16x32_bf16 v[32:35], v[176:179], v[192:195], v[32:35]
	v_mfma_f32_16x16x32_bf16 v[20:23], v[168:171], v[200:203], v[20:23]
	v_mfma_f32_16x16x32_bf16 v[16:19], v[176:179], v[200:203], v[16:19]
	v_mfma_f32_16x16x32_bf16 v[4:7], v[168:171], v[208:211], v[4:7]
	v_mfma_f32_16x16x32_bf16 v[0:3], v[176:179], v[208:211], v[0:3]
	v_mfma_f32_16x16x32_bf16 v[52:55], v[172:175], v[188:191], v[52:55]
	v_mfma_f32_16x16x32_bf16 v[48:51], v[180:183], v[188:191], v[48:51]
	v_mfma_f32_16x16x32_bf16 v[36:39], v[172:175], v[196:199], v[36:39]
	v_mfma_f32_16x16x32_bf16 v[32:35], v[180:183], v[196:199], v[32:35]
	v_mfma_f32_16x16x32_bf16 v[20:23], v[172:175], v[204:207], v[20:23]
	v_mfma_f32_16x16x32_bf16 v[16:19], v[180:183], v[204:207], v[16:19]
	v_mfma_f32_16x16x32_bf16 v[4:7], v[172:175], v[212:215], v[4:7]
	v_mfma_f32_16x16x32_bf16 v[0:3], v[180:183], v[212:215], v[0:3]
	s_setprio 0
	s_barrier
	s_add_i32 s54, s54, 2
	s_add_u32 s26, s26, 0x100
	s_addc_u32 s27, s27, 0
	s_add_u32 s25, s25, 0x100
	s_addc_u32 s53, s53, 0
	s_cmp_gt_u32 s54, 61
	s_cbranch_scc0 .LBB0_1369
	s_and_b64 vcc, exec, s[8:9]
	s_cbranch_vccz .LBB0_1372
	s_barrier

; #define PG8_STAGE(bufoff, gbase, voff) do { _Pragma("unroll") for (int _i = 0; _i < 2; ++_i) \
;         __builtin_amdgcn_global_load_lds((const unsigned*)((const char*)(gbase) + (voff)[_i]), (PG8_LAS unsigned*)(lds + (bufoff) + ldsw + _i * 8192), 16, 0, 0); } while (0)
; #define PG8_LDA(dst, b, h) do { _Pragma("unroll") for (int m = 0; m < 4; ++m) _Pragma("unroll") for (int k = 0; k < 2; ++k) dst[m][k] = *(const PG8_LAS bf16x8*)(lds + PG8_SA(b, h) + aoff + m * 2048 + k * 1024); } while (0)
; #define PG8_LDB(dst, b, h) do { _Pragma("unroll") for (int n = 0; n < 2; ++n) _Pragma("unroll") for (int k = 0; k < 2; ++k) dst[n][k] = *(const PG8_LAS bf16x8*)(lds + PG8_SB(b, h) + boff + n * 2048 + k * 1024); } while (0)
; #define PG8_MMA(ai, bj, At, Bt) do { __builtin_amdgcn_s_setprio(1); _Pragma("unroll") for (int m = 0; m < 4; ++m) _Pragma("unroll") for (int n = 0; n < 2; ++n) _Pragma("unroll") for (int k = 0; k < 2; ++k) \
;         acc[ai][bj][m][n] = __builtin_amdgcn_mfma_f32_16x16x32_bf16(Bt[n][k], At[m][k], acc[ai][bj][m][n], 0, 0, 0); __builtin_amdgcn_s_setprio(0); } while (0)
; #define PG8_WAIT_V(n) asm volatile("s_waitcnt vmcnt(" #n ")" ::: "memory")
; #define PG8_WAIT_L(n) asm volatile("s_waitcnt lgkmcnt(" #n ")" ::: "memory")
; template <class Epi, class Sched, bool ALIGN_EPI = false, bool SP2 = false>
; __device__ __forceinline__ void gemm_phase(PG8_LAS unsigned char* lds, const Gemm g, const Sched& S, const Epi& E, int tid_in) {
;     ...
;             const bool last = (t == nt - 2);
;             const char* a1 = cA + (size_t)(t + 1) * kstep;
;             const char* a2 = last ? nA : cA + (size_t)(t + 2) * kstep; const char* b2 = last ? nB : cB + (size_t)(t + 2) * kstep;
;             const char* a3 = a2 + kstep; const char* b3 = b2 + kstep;
;             if (last && has_next) S.a_ready(nxt);
;             if constexpr (SP2) {
;             PG8_LDB(B0, 0, 0); PG8_LDB(B1, 0, 1); PG8_SCHED; PG8_LDA(At, 0, 0); PG8_STAGE(PG8_SA(1, 1), a1 + hstep, voffA);
;             PG8_WAIT_V(8); PG8_WAIT_L(0); PG8_BAR; PG8_MMA(0, 0, At, B0); PG8_MMA(0, 1, At, B1); PG8_BAR; PG8_SCHED;
;             PG8_LDA(At, 0, 1); PG8_STAGE(PG8_SB(0, 0), b2, voffB); PG8_STAGE(PG8_SB(0, 1), b2 + hstep, voffB); PG8_STAGE(PG8_SA(0, 0), a2, voffA);
;             PG8_WAIT_V(8); PG8_WAIT_L(0); PG8_BAR; PG8_MMA(1, 0, At, B0); PG8_MMA(1, 1, At, B1); PG8_BAR; PG8_SCHED;
.LBB0_1551:
	s_mov_b64 vcc, s[8:9]
	ds_read_b128 v[150:153], v147
	ds_read_b128 v[154:157], v147 offset:1024
	ds_read_b128 v[158:161], v147 offset:2048
	ds_read_b128 v[162:165], v147 offset:3072
	s_cbranch_vccnz .Lb1a_1551_0
	ds_read_b128 v[166:169], v148
	ds_read_b128 v[170:173], v148 offset:1024
	ds_read_b128 v[174:177], v148 offset:2048
	ds_read_b128 v[178:181], v148 offset:3072
.Lb1a_1551_0:
	s_add_u32 s34, s30, 0xfff00080
	s_addc_u32 s35, s31, -1
	s_cmp_eq_u32 s60, 60
	s_cselect_b32 s37, s21, s35
	s_cselect_b32 s36, s56, s34
	s_cselect_b32 s35, s19, s59
	s_cselect_b32 s34, s57, s58
	v_lshl_add_u64 v[142:143], s[30:31], 0, v[136:137]
	s_add_i32 m0, s29, 0xc000
	ds_read_b128 v[182:185], v149
	ds_read_b128 v[186:189], v149 offset:1024
	ds_read_b128 v[190:193], v149 offset:2048
	ds_read_b128 v[194:197], v149 offset:3072
	ds_read_b128 v[198:201], v149 offset:4096
	ds_read_b128 v[202:205], v149 offset:5120
	ds_read_b128 v[206:209], v149 offset:6144
	ds_read_b128 v[210:213], v149 offset:7168
	global_load_lds_dwordx4 v[142:143], off
	v_lshl_add_u64 v[142:143], s[30:31], 0, v[138:139]
	s_add_i32 m0, s29, 0xe000
	s_nop 0
	global_load_lds_dwordx4 v[142:143], off
	s_waitcnt vmcnt(8)
	s_waitcnt lgkmcnt(0)
	s_barrier
	s_setprio 1
	s_waitcnt lgkmcnt(0)
	s_cbranch_vccz .Lb1b_1551_0
	ds_read_b128 v[166:169], v148
	ds_read_b128 v[170:173], v148 offset:1024
	ds_read_b128 v[174:177], v148 offset:2048
	ds_read_b128 v[178:181], v148 offset:3072
.Lb1b_1551_0:
	v_mfma_f32_16x16x32_bf16 v[124:127], v[150:153], v[182:185], v[124:127]
	v_mfma_f32_16x16x32_bf16 v[120:123], v[158:161], v[182:185], v[120:123]
	v_mfma_f32_16x16x32_bf16 v[112:115], v[150:153], v[190:193], v[112:115]
	v_mfma_f32_16x16x32_bf16 v[104:107], v[158:161], v[190:193], v[104:107]
	v_mfma_f32_16x16x32_bf16 v[96:99], v[150:153], v[198:201], v[96:99]
	v_mfma_f32_16x16x32_bf16 v[88:91], v[158:161], v[198:201], v[88:91]
	v_mfma_f32_16x16x32_bf16 v[80:83], v[150:153], v[206:209], v[80:83]
	v_mfma_f32_16x16x32_bf16 v[72:75], v[158:161], v[206:209], v[72:75]
	v_mfma_f32_16x16x32_bf16 v[124:127], v[154:157], v[186:189], v[124:127]
	v_mfma_f32_16x16x32_bf16 v[120:123], v[162:165], v[186:189], v[120:123]
	v_mfma_f32_16x16x32_bf16 v[112:115], v[154:157], v[194:197], v[112:115]
	v_mfma_f32_16x16x32_bf16 v[104:107], v[162:165], v[194:197], v[104:107]
	v_mfma_f32_16x16x32_bf16 v[96:99], v[154:157], v[202:205], v[96:99]
	v_mfma_f32_16x16x32_bf16 v[88:91], v[162:165], v[202:205], v[88:91]
	v_mfma_f32_16x16x32_bf16 v[80:83], v[154:157], v[210:213], v[80:83]
	v_mfma_f32_16x16x32_bf16 v[72:75], v[162:165], v[210:213], v[72:75]
	s_setprio 0
	s_setprio 1
	s_waitcnt lgkmcnt(0)
	v_mfma_f32_16x16x32_bf16 v[116:119], v[166:169], v[182:185], v[116:119]
	v_mfma_f32_16x16x32_bf16 v[108:111], v[174:177], v[182:185], v[108:111]
	v_mfma_f32_16x16x32_bf16 v[100:103], v[166:169], v[190:193], v[100:103]
	v_mfma_f32_16x16x32_bf16 v[92:95], v[174:177], v[190:193], v[92:95]
	v_mfma_f32_16x16x32_bf16 v[84:87], v[166:169], v[198:201], v[84:87]
	v_mfma_f32_16x16x32_bf16 v[76:79], v[174:177], v[198:201], v[76:79]
	v_mfma_f32_16x16x32_bf16 v[68:71], v[166:169], v[206:209], v[68:71]
	v_mfma_f32_16x16x32_bf16 v[64:67], v[174:177], v[206:209], v[64:67]
	v_mfma_f32_16x16x32_bf16 v[116:119], v[170:173], v[186:189], v[116:119]
	v_mfma_f32_16x16x32_bf16 v[108:111], v[178:181], v[186:189], v[108:111]
	v_mfma_f32_16x16x32_bf16 v[100:103], v[170:173], v[194:197], v[100:103]
	v_mfma_f32_16x16x32_bf16 v[92:95], v[178:181], v[194:197], v[92:95]
	v_mfma_f32_16x16x32_bf16 v[84:87], v[170:173], v[202:205], v[84:87]
	v_mfma_f32_16x16x32_bf16 v[76:79], v[178:181], v[202:205], v[76:79]
	v_mfma_f32_16x16x32_bf16 v[68:71], v[170:173], v[210:213], v[68:71]
	v_mfma_f32_16x16x32_bf16 v[64:67], v[178:181], v[210:213], v[64:67]
	s_setprio 0
	s_barrier
	s_add_i32 s61, s49, s40
	v_lshl_add_u64 v[142:143], s[34:35], 0, v[132:133]
	s_mov_b32 m0, s61
	ds_read_b128 v[182:185], v149 offset:16384
	ds_read_b128 v[186:189], v149 offset:17408
	ds_read_b128 v[190:193], v149 offset:18432
	ds_read_b128 v[194:197], v149 offset:19456
	ds_read_b128 v[198:201], v149 offset:20480
	ds_read_b128 v[202:205], v149 offset:21504
	ds_read_b128 v[206:209], v149 offset:22528
	ds_read_b128 v[210:213], v149 offset:23552
	global_load_lds_dwordx4 v[142:143], off
	s_add_i32 m0, s61, 0x2000
	s_add_u32 s62, s34, 0x100000
	v_lshl_add_u64 v[214:215], s[34:35], 0, v[128:129]
	s_addc_u32 s63, s35, 0
	s_add_i32 s61, s50, s40
	global_load_lds_dwordx4 v[214:215], off
	v_lshl_add_u64 v[216:217], s[62:63], 0, v[132:133]
	s_mov_b32 m0, s61
	v_lshl_add_u64 v[218:219], s[36:37], 0, v[130:131]
	global_load_lds_dwordx4 v[216:217], off
	v_lshl_add_u64 v[216:217], s[62:63], 0, v[128:129]
	s_add_i32 m0, s61, 0x2000
	s_nop 0
	global_load_lds_dwordx4 v[216:217], off
	v_lshl_add_u64 v[216:217], s[36:37], 0, v[134:135]
	s_mov_b32 m0, s29
	s_nop 0
	global_load_lds_dwordx4 v[216:217], off
	s_mov_b32 m0, s43
	s_nop 0
	global_load_lds_dwordx4 v[218:219], off
	s_waitcnt vmcnt(8)
	s_waitcnt lgkmcnt(0)
	s_barrier
; #define PG8_STAGE(bufoff, gbase, voff) do { _Pragma("unroll") for (int _i = 0; _i < 2; ++_i) \
;         __builtin_amdgcn_global_load_lds((const unsigned*)((const char*)(gbase) + (voff)[_i]), (PG8_LAS unsigned*)(lds + (bufoff) + ldsw + _i * 8192), 16, 0, 0); } while (0)
; #define PG8_LDA(dst, b, h) do { _Pragma("unroll") for (int m = 0; m < 4; ++m) _Pragma("unroll") for (int k = 0; k < 2; ++k) dst[m][k] = *(const PG8_LAS bf16x8*)(lds + PG8_SA(b, h) + aoff + m * 2048 + k * 1024); } while (0)
; #define PG8_LDB(dst, b, h) do { _Pragma("unroll") for (int n = 0; n < 2; ++n) _Pragma("unroll") for (int k = 0; k < 2; ++k) dst[n][k] = *(const PG8_LAS bf16x8*)(lds + PG8_SB(b, h) + boff + n * 2048 + k * 1024); } while (0)
; #define PG8_MMA(ai, bj, At, Bt) do { __builtin_amdgcn_s_setprio(1); _Pragma("unroll") for (int m = 0; m < 4; ++m) _Pragma("unroll") for (int n = 0; n < 2; ++n) _Pragma("unroll") for (int k = 0; k < 2; ++k) \
;         acc[ai][bj][m][n] = __builtin_amdgcn_mfma_f32_16x16x32_bf16(Bt[n][k], At[m][k], acc[ai][bj][m][n], 0, 0, 0); __builtin_amdgcn_s_setprio(0); } while (0)
; #define PG8_WAIT_V(n) asm volatile("s_waitcnt vmcnt(" #n ")" ::: "memory")
; #define PG8_WAIT_L(n) asm volatile("s_waitcnt lgkmcnt(" #n ")" ::: "memory")
; #define PG8_BAR __builtin_amdgcn_s_barrier()
; #define PG8_SCHED __builtin_amdgcn_sched_barrier(0)
; template <class Epi, class Sched, bool ALIGN_EPI = false, bool SP2 = false>
; __device__ __forceinline__ void gemm_phase(PG8_LAS unsigned char* lds, const Gemm g, const Sched& S, const Epi& E, int tid_in) {
;     ...
;             PG8_WAIT_V(8); PG8_WAIT_L(0); PG8_BAR; PG8_MMA(1, 0, At, B0); PG8_MMA(1, 1, At, B1); PG8_BAR; PG8_SCHED;
;             PG8_LDB(B0, 1, 0); PG8_LDB(B1, 1, 1); PG8_SCHED; PG8_LDA(At, 1, 0); PG8_STAGE(PG8_SA(0, 1), a2 + hstep, voffA);
;             PG8_WAIT_V(8); PG8_WAIT_L(0); PG8_BAR; PG8_MMA(0, 0, At, B0); PG8_MMA(0, 1, At, B1); PG8_BAR; PG8_SCHED;
	s_setprio 1
	s_waitcnt lgkmcnt(0)
	v_mfma_f32_16x16x32_bf16 v[60:63], v[150:153], v[182:185], v[60:63]
	v_mfma_f32_16x16x32_bf16 v[56:59], v[158:161], v[182:185], v[56:59]
	v_mfma_f32_16x16x32_bf16 v[48:51], v[150:153], v[190:193], v[48:51]
	v_mfma_f32_16x16x32_bf16 v[40:43], v[158:161], v[190:193], v[40:43]
	v_mfma_f32_16x16x32_bf16 v[32:35], v[150:153], v[198:201], v[32:35]
	v_mfma_f32_16x16x32_bf16 v[24:27], v[158:161], v[198:201], v[24:27]
	v_mfma_f32_16x16x32_bf16 v[16:19], v[150:153], v[206:209], v[16:19]
	v_mfma_f32_16x16x32_bf16 v[8:11], v[158:161], v[206:209], v[8:11]
	v_mfma_f32_16x16x32_bf16 v[60:63], v[154:157], v[186:189], v[60:63]
	v_mfma_f32_16x16x32_bf16 v[56:59], v[162:165], v[186:189], v[56:59]
	v_mfma_f32_16x16x32_bf16 v[48:51], v[154:157], v[194:197], v[48:51]
	v_mfma_f32_16x16x32_bf16 v[40:43], v[162:165], v[194:197], v[40:43]
	v_mfma_f32_16x16x32_bf16 v[32:35], v[154:157], v[202:205], v[32:35]
	v_mfma_f32_16x16x32_bf16 v[24:27], v[162:165], v[202:205], v[24:27]
	v_mfma_f32_16x16x32_bf16 v[16:19], v[154:157], v[210:213], v[16:19]
	v_mfma_f32_16x16x32_bf16 v[8:11], v[162:165], v[210:213], v[8:11]
	s_setprio 0
	s_setprio 1
	v_mfma_f32_16x16x32_bf16 v[52:55], v[166:169], v[182:185], v[52:55]
	v_mfma_f32_16x16x32_bf16 v[44:47], v[174:177], v[182:185], v[44:47]
	v_mfma_f32_16x16x32_bf16 v[36:39], v[166:169], v[190:193], v[36:39]
	v_mfma_f32_16x16x32_bf16 v[28:31], v[174:177], v[190:193], v[28:31]
	v_mfma_f32_16x16x32_bf16 v[20:23], v[166:169], v[198:201], v[20:23]
	v_mfma_f32_16x16x32_bf16 v[12:15], v[174:177], v[198:201], v[12:15]
	v_mfma_f32_16x16x32_bf16 v[4:7], v[166:169], v[206:209], v[4:7]
	v_mfma_f32_16x16x32_bf16 v[0:3], v[174:177], v[206:209], v[0:3]
	v_mfma_f32_16x16x32_bf16 v[52:55], v[170:173], v[186:189], v[52:55]
	v_mfma_f32_16x16x32_bf16 v[44:47], v[178:181], v[186:189], v[44:47]
	v_mfma_f32_16x16x32_bf16 v[36:39], v[170:173], v[194:197], v[36:39]
	v_mfma_f32_16x16x32_bf16 v[28:31], v[178:181], v[194:197], v[28:31]
	v_mfma_f32_16x16x32_bf16 v[20:23], v[170:173], v[202:205], v[20:23]
	v_mfma_f32_16x16x32_bf16 v[12:15], v[178:181], v[202:205], v[12:15]
	v_mfma_f32_16x16x32_bf16 v[4:7], v[170:173], v[210:213], v[4:7]
	v_mfma_f32_16x16x32_bf16 v[0:3], v[178:181], v[210:213], v[0:3]
	s_setprio 0
	s_barrier
	s_add_i32 s61, 0, 0x18000
	s_add_i32 s62, 0, 0x1c000
	v_add_u32_e32 v162, s61, v145
	v_add_u32_e32 v178, s62, v145
	ds_read_b128 v[150:153], v162
	ds_read_b128 v[154:157], v162 offset:1024
	ds_read_b128 v[158:161], v162 offset:2048
	ds_read_b128 v[162:165], v162 offset:3072
	s_cbranch_vccnz .Lb1a_1551_1
	ds_read_b128 v[166:169], v178
	ds_read_b128 v[170:173], v178 offset:1024
	ds_read_b128 v[174:177], v178 offset:2048
	ds_read_b128 v[178:181], v178 offset:3072
.Lb1a_1551_1:
	s_add_u32 s36, s36, 0x100000
	s_addc_u32 s37, s37, 0
	s_mov_b32 m0, s44
	v_lshl_add_u64 v[220:221], s[36:37], 0, v[134:135]
	ds_read_b128 v[182:185], v149 offset:32768
	ds_read_b128 v[186:189], v149 offset:33792
	ds_read_b128 v[190:193], v149 offset:34816
	ds_read_b128 v[194:197], v149 offset:35840
	ds_read_b128 v[198:201], v149 offset:36864
	ds_read_b128 v[202:205], v149 offset:37888
	ds_read_b128 v[206:209], v149 offset:38912
	ds_read_b128 v[210:213], v149 offset:39936
	global_load_lds_dwordx4 v[220:221], off
	v_lshl_add_u64 v[220:221], s[36:37], 0, v[130:131]
	s_mov_b32 m0, s45
	s_nop 0
	global_load_lds_dwordx4 v[220:221], off
	s_waitcnt vmcnt(8)
	s_waitcnt lgkmcnt(0)
	s_barrier
	s_setprio 1
	s_waitcnt lgkmcnt(0)
	s_cbranch_vccz .Lb1b_1551_1
	ds_read_b128 v[166:169], v178
	ds_read_b128 v[170:173], v178 offset:1024
	ds_read_b128 v[174:177], v178 offset:2048
	ds_read_b128 v[178:181], v178 offset:3072
; #define PG8_STAGE(bufoff, gbase, voff) do { _Pragma("unroll") for (int _i = 0; _i < 2; ++_i) \
;         __builtin_amdgcn_global_load_lds((const unsigned*)((const char*)(gbase) + (voff)[_i]), (PG8_LAS unsigned*)(lds + (bufoff) + ldsw + _i * 8192), 16, 0, 0); } while (0)
; #define PG8_LDA(dst, b, h) do { _Pragma("unroll") for (int m = 0; m < 4; ++m) _Pragma("unroll") for (int k = 0; k < 2; ++k) dst[m][k] = *(const PG8_LAS bf16x8*)(lds + PG8_SA(b, h) + aoff + m * 2048 + k * 1024); } while (0)
; #define PG8_MMA(ai, bj, At, Bt) do { __builtin_amdgcn_s_setprio(1); _Pragma("unroll") for (int m = 0; m < 4; ++m) _Pragma("unroll") for (int n = 0; n < 2; ++n) _Pragma("unroll") for (int k = 0; k < 2; ++k) \
;         acc[ai][bj][m][n] = __builtin_amdgcn_mfma_f32_16x16x32_bf16(Bt[n][k], At[m][k], acc[ai][bj][m][n], 0, 0, 0); __builtin_amdgcn_s_setprio(0); } while (0)
; #define PG8_WAIT_V(n) asm volatile("s_waitcnt vmcnt(" #n ")" ::: "memory")
; #define PG8_WAIT_L(n) asm volatile("s_waitcnt lgkmcnt(" #n ")" ::: "memory")
; #define PG8_BAR __builtin_amdgcn_s_barrier()
; #define PG8_SCHED __builtin_amdgcn_sched_barrier(0)
; template <class Epi, class Sched, bool ALIGN_EPI = false, bool SP2 = false>
; __device__ __forceinline__ void gemm_phase(PG8_LAS unsigned char* lds, const Gemm g, const Sched& S, const Epi& E, int tid_in) {
;     ...
;             PG8_WAIT_V(8); PG8_WAIT_L(0); PG8_BAR; PG8_MMA(0, 0, At, B0); PG8_MMA(0, 1, At, B1); PG8_BAR; PG8_SCHED;
;             PG8_LDA(At, 1, 1); PG8_STAGE(PG8_SB(1, 0), b3, voffB); PG8_STAGE(PG8_SB(1, 1), b3 + hstep, voffB); PG8_STAGE(PG8_SA(1, 0), a3, voffA);
;             PG8_WAIT_V(8); PG8_WAIT_L(0); PG8_BAR; PG8_MMA(1, 0, At, B0); PG8_MMA(1, 1, At, B1); PG8_BAR; PG8_SCHED;
.Lb1b_1551_1:
	v_mfma_f32_16x16x32_bf16 v[124:127], v[150:153], v[182:185], v[124:127]
	v_mfma_f32_16x16x32_bf16 v[120:123], v[158:161], v[182:185], v[120:123]
	v_mfma_f32_16x16x32_bf16 v[112:115], v[150:153], v[190:193], v[112:115]
	v_mfma_f32_16x16x32_bf16 v[104:107], v[158:161], v[190:193], v[104:107]
	v_mfma_f32_16x16x32_bf16 v[96:99], v[150:153], v[198:201], v[96:99]
	v_mfma_f32_16x16x32_bf16 v[88:91], v[158:161], v[198:201], v[88:91]
	v_mfma_f32_16x16x32_bf16 v[80:83], v[150:153], v[206:209], v[80:83]
	v_mfma_f32_16x16x32_bf16 v[72:75], v[158:161], v[206:209], v[72:75]
	v_mfma_f32_16x16x32_bf16 v[124:127], v[154:157], v[186:189], v[124:127]
	v_mfma_f32_16x16x32_bf16 v[120:123], v[162:165], v[186:189], v[120:123]
	v_mfma_f32_16x16x32_bf16 v[112:115], v[154:157], v[194:197], v[112:115]
	v_mfma_f32_16x16x32_bf16 v[104:107], v[162:165], v[194:197], v[104:107]
	v_mfma_f32_16x16x32_bf16 v[96:99], v[154:157], v[202:205], v[96:99]
	v_mfma_f32_16x16x32_bf16 v[88:91], v[162:165], v[202:205], v[88:91]
	v_mfma_f32_16x16x32_bf16 v[80:83], v[154:157], v[210:213], v[80:83]
	v_mfma_f32_16x16x32_bf16 v[72:75], v[162:165], v[210:213], v[72:75]
	s_setprio 0
	s_setprio 1
	s_waitcnt lgkmcnt(0)
	v_mfma_f32_16x16x32_bf16 v[116:119], v[166:169], v[182:185], v[116:119]
	v_mfma_f32_16x16x32_bf16 v[108:111], v[174:177], v[182:185], v[108:111]
	v_mfma_f32_16x16x32_bf16 v[100:103], v[166:169], v[190:193], v[100:103]
	v_mfma_f32_16x16x32_bf16 v[92:95], v[174:177], v[190:193], v[92:95]
	v_mfma_f32_16x16x32_bf16 v[84:87], v[166:169], v[198:201], v[84:87]
	v_mfma_f32_16x16x32_bf16 v[76:79], v[174:177], v[198:201], v[76:79]
	v_mfma_f32_16x16x32_bf16 v[68:71], v[166:169], v[206:209], v[68:71]
	v_mfma_f32_16x16x32_bf16 v[64:67], v[174:177], v[206:209], v[64:67]
	v_mfma_f32_16x16x32_bf16 v[116:119], v[170:173], v[186:189], v[116:119]
	v_mfma_f32_16x16x32_bf16 v[108:111], v[178:181], v[186:189], v[108:111]
	v_mfma_f32_16x16x32_bf16 v[100:103], v[170:173], v[194:197], v[100:103]
	v_mfma_f32_16x16x32_bf16 v[92:95], v[178:181], v[194:197], v[92:95]
	v_mfma_f32_16x16x32_bf16 v[84:87], v[170:173], v[202:205], v[84:87]
	v_mfma_f32_16x16x32_bf16 v[76:79], v[178:181], v[202:205], v[76:79]
	v_mfma_f32_16x16x32_bf16 v[68:71], v[170:173], v[210:213], v[68:71]
	v_mfma_f32_16x16x32_bf16 v[64:67], v[178:181], v[210:213], v[64:67]
	s_setprio 0
	s_barrier
	s_add_i32 s36, s61, s40
	v_lshl_add_u64 v[142:143], v[142:143], 0, s[6:7]
	s_mov_b32 m0, s36
	ds_read_b128 v[182:185], v149 offset:49152
	ds_read_b128 v[186:189], v149 offset:50176
	ds_read_b128 v[190:193], v149 offset:51200
	ds_read_b128 v[194:197], v149 offset:52224
	ds_read_b128 v[198:201], v149 offset:53248
	ds_read_b128 v[202:205], v149 offset:54272
	ds_read_b128 v[206:209], v149 offset:55296
	ds_read_b128 v[210:213], v149 offset:56320
	global_load_lds_dwordx4 v[142:143], off
	s_add_i32 m0, s36, 0x2000
	s_add_u32 s34, s34, 0x100080
	v_lshl_add_u64 v[142:143], v[214:215], 0, s[6:7]
	s_addc_u32 s35, s35, 0
	s_add_i32 s36, s62, s40
	global_load_lds_dwordx4 v[142:143], off
	v_lshl_add_u64 v[142:143], s[34:35], 0, v[132:133]
	s_mov_b32 m0, s36
	s_nop 0
	global_load_lds_dwordx4 v[142:143], off
	v_lshl_add_u64 v[142:143], s[34:35], 0, v[128:129]
	s_add_i32 m0, s36, 0x2000
	s_nop 0
	global_load_lds_dwordx4 v[142:143], off
	v_lshl_add_u64 v[142:143], v[216:217], 0, s[6:7]
	s_mov_b32 m0, s47
	s_nop 0
	global_load_lds_dwordx4 v[142:143], off
	v_lshl_add_u64 v[142:143], v[218:219], 0, s[6:7]
	s_mov_b32 m0, s48
	s_nop 0
	global_load_lds_dwordx4 v[142:143], off
	s_waitcnt vmcnt(8)
	s_waitcnt lgkmcnt(0)
	s_barrier
	s_setprio 1
	s_waitcnt lgkmcnt(0)
	v_mfma_f32_16x16x32_bf16 v[60:63], v[150:153], v[182:185], v[60:63]
	v_mfma_f32_16x16x32_bf16 v[56:59], v[158:161], v[182:185], v[56:59]
	v_mfma_f32_16x16x32_bf16 v[48:51], v[150:153], v[190:193], v[48:51]
	v_mfma_f32_16x16x32_bf16 v[40:43], v[158:161], v[190:193], v[40:43]
	v_mfma_f32_16x16x32_bf16 v[32:35], v[150:153], v[198:201], v[32:35]
	v_mfma_f32_16x16x32_bf16 v[24:27], v[158:161], v[198:201], v[24:27]
	v_mfma_f32_16x16x32_bf16 v[16:19], v[150:153], v[206:209], v[16:19]
	v_mfma_f32_16x16x32_bf16 v[8:11], v[158:161], v[206:209], v[8:11]
	v_mfma_f32_16x16x32_bf16 v[60:63], v[154:157], v[186:189], v[60:63]
	v_mfma_f32_16x16x32_bf16 v[56:59], v[162:165], v[186:189], v[56:59]
	v_mfma_f32_16x16x32_bf16 v[48:51], v[154:157], v[194:197], v[48:51]
	v_mfma_f32_16x16x32_bf16 v[40:43], v[162:165], v[194:197], v[40:43]
	v_mfma_f32_16x16x32_bf16 v[32:35], v[154:157], v[202:205], v[32:35]
	v_mfma_f32_16x16x32_bf16 v[24:27], v[162:165], v[202:205], v[24:27]
	v_mfma_f32_16x16x32_bf16 v[16:19], v[154:157], v[210:213], v[16:19]
	v_mfma_f32_16x16x32_bf16 v[8:11], v[162:165], v[210:213], v[8:11]
	s_setprio 0
	s_setprio 1
	v_mfma_f32_16x16x32_bf16 v[52:55], v[166:169], v[182:185], v[52:55]
	v_mfma_f32_16x16x32_bf16 v[44:47], v[174:177], v[182:185], v[44:47]
	v_mfma_f32_16x16x32_bf16 v[36:39], v[166:169], v[190:193], v[36:39]
	v_mfma_f32_16x16x32_bf16 v[28:31], v[174:177], v[190:193], v[28:31]
	v_mfma_f32_16x16x32_bf16 v[20:23], v[166:169], v[198:201], v[20:23]
	v_mfma_f32_16x16x32_bf16 v[12:15], v[174:177], v[198:201], v[12:15]
	v_mfma_f32_16x16x32_bf16 v[4:7], v[166:169], v[206:209], v[4:7]
	v_mfma_f32_16x16x32_bf16 v[0:3], v[174:177], v[206:209], v[0:3]
	v_mfma_f32_16x16x32_bf16 v[52:55], v[170:173], v[186:189], v[52:55]
	v_mfma_f32_16x16x32_bf16 v[44:47], v[178:181], v[186:189], v[44:47]
	v_mfma_f32_16x16x32_bf16 v[36:39], v[170:173], v[194:197], v[36:39]
	v_mfma_f32_16x16x32_bf16 v[28:31], v[178:181], v[194:197], v[28:31]
	v_mfma_f32_16x16x32_bf16 v[20:23], v[170:173], v[202:205], v[20:23]
	v_mfma_f32_16x16x32_bf16 v[12:15], v[178:181], v[202:205], v[12:15]
	v_mfma_f32_16x16x32_bf16 v[4:7], v[170:173], v[210:213], v[4:7]
	v_mfma_f32_16x16x32_bf16 v[0:3], v[178:181], v[210:213], v[0:3]
	s_setprio 0
	s_barrier
	s_add_i32 s60, s60, 2
	s_add_u32 s30, s30, 0x100
	s_addc_u32 s31, s31, 0
	s_add_u32 s58, s58, 0x100
	s_addc_u32 s59, s59, 0
	s_cmp_gt_u32 s60, 61
	s_cbranch_scc0 .LBB0_1551
	s_and_b64 vcc, exec, s[8:9]
	s_cbranch_vccz .LBB0_1554
	s_barrier
